# attention: K/V tiles prefetched two tiles ahead through a second register set; diagonal tile no longer drains the prefetch; plus x->f16 loop
# baseline (speedup 1.0000x reference)
; #define LAS __attribute__((address_space(3)))
; __device__ __forceinline__ void attn_phase(LAS unsigned char* lds, const bf16* Q, const bf16* K, const bf16* V, bf16* O, int cu, int G, int rev) {
;     ...
;         const int idx = cu * 8 + wid + 2048 * (k & 3), b = 4 * (idx & 7) + (rev ? 3 - (k >> 2) : (k >> 2)), h = (idx >> 3) & 15, qb = idx >> 7;
;         const size_t rowbase = (size_t)b * SEQ;
;         const int q0w = qb * 32;
;         bf16x8 qf[4];
;         { const bf16* qp = Q + (rowbase + q0w + q32) * DM + h * HD + hi * 8;
; #pragma unroll
;           for (int ks = 0; ks < 4; ++ks) qf[ks] = *(const bf16x8*)(qp + ks * 16); }
;         f32x16 o0, o1;
; #pragma unroll
;         for (int r = 0; r < 16; ++r) { o0[r] = 0.f; o1[r] = 0.f; }
;         float R = 0.f;
;         const bf16* kp = K + (rowbase + lkey) * DM + h * HD + lch * 8;
;         const bf16* vp = V + (rowbase + lkey) * DM + h * HD + lch * 8;
;         u32x4 kr[4], vr[4];
; #pragma unroll
;         for (int jj = 0; jj < 4; ++jj) { kr[jj] = *(const u32x4*)(kp + (size_t)(q0w + 8 * jj) * DM); vr[jj] = *(const u32x4*)(vp + (size_t)(q0w + 8 * jj) * DM); }
;         for (int key0 = q0w; key0 >= 0; key0 -= 32) {
; #pragma unroll
;             for (int jj = 0; jj < 4; ++jj) { *(LAS u32x4*)(Ks + (lkey + 8 * jj) * 144 + lch * 16) = kr[jj]; *(LAS u32x4*)(Vs + (lkey + 8 * jj) * 192 + lch * 16) = vr[jj]; }
;             asm volatile("s_waitcnt lgkmcnt(0)" ::: "memory");
;             if (key0 >= 32) {
; #pragma unroll
;                 for (int jj = 0; jj < 4; ++jj) { kr[jj] = *(const u32x4*)(kp + (size_t)(key0 - 32 + 8 * jj) * DM); vr[jj] = *(const u32x4*)(vp + (size_t)(key0 - 32 + 8 * jj) * DM); } }
.LBB0_301:
	s_lshl_b32 s44, s61, 11
	s_and_b32 s44, s44, 0x1800
	s_add_i32 s51, s44, s53
	s_lshr_b32 s44, s61, 2
	s_sub_i32 s64, 3, s44
	s_and_b64 s[62:63], s[58:59], exec
	s_cselect_b32 s44, s44, s64
	s_ashr_i32 s91, s51, 2
	s_or_b32 s44, s44, s60
	s_and_b32 s62, s91, 0xffffffe0
	s_lshl_b32 s44, s44, 11
	s_ashr_i32 s63, s62, 31
	s_add_u32 s67, s44, s62
	s_addc_u32 s76, 0, s63
	s_cmp_lt_i32 s91, 0
	s_cbranch_scc1 .LBB0_299
	v_or_b32_e32 v0, s44, v100
	v_lshlrev_b32_e32 v2, 11, v0
	v_mov_b32_e32 v3, v48
	s_or_b32 s44, s62, 24
	v_lshl_add_u64 v[118:119], v[106:107], 0, v[2:3]
	v_lshl_add_u64 v[120:121], v[108:109], 0, v[2:3]
	s_lshl_b64 s[64:65], s[44:45], 11
	s_or_b32 s44, s62, 16
	v_lshl_add_u64 v[2:3], v[120:121], 0, s[64:65]
	v_lshl_add_u64 v[4:5], v[118:119], 0, s[64:65]
	s_lshl_b64 s[64:65], s[44:45], 11
	s_or_b32 s44, s62, 8
	v_lshl_add_u64 v[6:7], v[120:121], 0, s[64:65]
	v_lshl_add_u64 v[8:9], v[118:119], 0, s[64:65]
	s_lshl_b64 s[64:65], s[44:45], 11
	v_lshl_add_u64 v[10:11], v[120:121], 0, s[64:65]
	v_lshl_add_u64 v[12:13], v[118:119], 0, s[64:65]
	s_lshl_b64 s[64:65], s[62:63], 11
	v_mov_b32_e32 v1, s76
	v_lshl_add_u64 v[14:15], v[120:121], 0, s[64:65]
	v_or_b32_e32 v0, s67, v98
	v_lshl_add_u64 v[16:17], v[118:119], 0, s[64:65]
	global_load_dwordx4 v[70:73], v[14:15], off
	global_load_dwordx4 v[66:69], v[16:17], off
	global_load_dwordx4 v[78:81], v[10:11], off
	global_load_dwordx4 v[74:77], v[12:13], off
	global_load_dwordx4 v[86:89], v[6:7], off
	global_load_dwordx4 v[82:85], v[8:9], off
	global_load_dwordx4 v[94:97], v[2:3], off
	global_load_dwordx4 v[90:93], v[4:5], off
	v_lshlrev_b64 v[0:1], 11, v[0:1]
	v_lshl_add_u64 v[0:1], v[104:105], 0, v[0:1]
	global_load_dwordx4 v[50:53], v[0:1], off
	global_load_dwordx4 v[54:57], v[0:1], off offset:32
	global_load_dwordx4 v[58:61], v[0:1], off offset:64
	global_load_dwordx4 v[62:65], v[0:1], off offset:96
	s_cmp_gt_u32 s91, 31
	s_cselect_b64 s[64:65], -1, 0
	s_cmp_lt_u32 s91, 32
	s_waitcnt vmcnt(10)
	ds_write_b128 v101, v[66:69]
	ds_write_b128 v103, v[70:73] offset:4608
	s_waitcnt vmcnt(8)
	ds_write_b128 v101, v[74:77] offset:1152
	ds_write_b128 v103, v[78:81] offset:6144
	s_waitcnt vmcnt(6)
	ds_write_b128 v101, v[82:85] offset:2304
	ds_write_b128 v103, v[86:89] offset:7680
	s_waitcnt vmcnt(4)
	ds_write_b128 v101, v[90:93] offset:3456
	ds_write_b128 v103, v[94:97] offset:9216
	s_waitcnt lgkmcnt(0)
	s_waitcnt vmcnt(0)
	s_cbranch_scc1 .LBB0_304
	s_sub_i32 s44, s62, 32
	s_lshl_b64 s[96:97], s[44:45], 11
	v_lshl_add_u64 v[0:1], v[118:119], 0, s[96:97]
	v_lshl_add_u64 v[2:3], v[120:121], 0, s[96:97]
	global_load_dwordx4 v[208:211], v[0:1], off
	global_load_dwordx4 v[212:215], v[2:3], off
	s_sub_i32 s44, s62, 24
	s_lshl_b64 s[96:97], s[44:45], 11
	v_lshl_add_u64 v[0:1], v[118:119], 0, s[96:97]
	v_lshl_add_u64 v[2:3], v[120:121], 0, s[96:97]
	global_load_dwordx4 v[216:219], v[0:1], off
	global_load_dwordx4 v[220:223], v[2:3], off
	s_sub_i32 s44, s62, 16
	s_lshl_b64 s[96:97], s[44:45], 11
	v_lshl_add_u64 v[0:1], v[118:119], 0, s[96:97]
	v_lshl_add_u64 v[2:3], v[120:121], 0, s[96:97]
	global_load_dwordx4 v[224:227], v[0:1], off
	global_load_dwordx4 v[228:231], v[2:3], off
	s_sub_i32 s44, s62, 8
	s_lshl_b64 s[96:97], s[44:45], 11
	v_lshl_add_u64 v[0:1], v[118:119], 0, s[96:97]
	v_lshl_add_u64 v[2:3], v[120:121], 0, s[96:97]
	global_load_dwordx4 v[232:235], v[0:1], off
	global_load_dwordx4 v[236:239], v[2:3], off
	s_cmp_lt_i32 s62, 64
	s_cbranch_scc1 .LBB0_304
	s_sub_i32 s44, s62, 64
	s_lshl_b64 s[96:97], s[44:45], 11
	v_lshl_add_u64 v[0:1], v[118:119], 0, s[96:97]
	v_lshl_add_u64 v[2:3], v[120:121], 0, s[96:97]
	global_load_dwordx4 v[66:69], v[0:1], off
	global_load_dwordx4 v[70:73], v[2:3], off
	s_sub_i32 s44, s62, 56
	s_lshl_b64 s[96:97], s[44:45], 11
	v_lshl_add_u64 v[0:1], v[118:119], 0, s[96:97]
	v_lshl_add_u64 v[2:3], v[120:121], 0, s[96:97]
	global_load_dwordx4 v[74:77], v[0:1], off
	global_load_dwordx4 v[78:81], v[2:3], off
	s_sub_i32 s44, s62, 48
	s_lshl_b64 s[96:97], s[44:45], 11
	v_lshl_add_u64 v[0:1], v[118:119], 0, s[96:97]
	v_lshl_add_u64 v[2:3], v[120:121], 0, s[96:97]
	global_load_dwordx4 v[82:85], v[0:1], off
	global_load_dwordx4 v[86:89], v[2:3], off
	s_sub_i32 s44, s62, 40
	s_lshl_b64 s[96:97], s[44:45], 11
	v_lshl_add_u64 v[0:1], v[118:119], 0, s[96:97]
	v_lshl_add_u64 v[2:3], v[120:121], 0, s[96:97]
	global_load_dwordx4 v[90:93], v[0:1], off
	global_load_dwordx4 v[94:97], v[2:3], off
; #define LAS __attribute__((address_space(3)))
; __device__ __forceinline__ void attn_phase(LAS unsigned char* lds, const bf16* Q, const bf16* K, const bf16* V, bf16* O, int cu, int G, int rev) {
;     ...
;             const bool diag = (key0 == q0w);
;             f32x16 s;
; #pragma unroll
;             for (int r = 0; r < 16; ++r) s[r] = 0.f;
; #pragma unroll
;             for (int ks = 0; ks < 4; ++ks) { const bf16x8 kf = *(LAS const bf16x8*)(Ks + q32 * 144 + (16 * ks + 8 * hi) * 2);
;                 s = __builtin_amdgcn_mfma_f32_32x32x16_bf16(kf, qf[ks], s, 0, 0, 0); }
;             float zs[16], l1[16];
; #pragma unroll
;             for (int r = 0; r < 16; ++r) { const float z = s[r] * LOG2E; const float e = __builtin_amdgcn_exp2f(-__builtin_fabsf(z)); const float t = __builtin_amdgcn_logf(1.0f + e);
;                 float l = -(__builtin_fmaxf(z, 0.f) + t);
;                 if (diag) { const int kl = 8 * (r >> 2) + 4 * hi + (r & 3); if (kl >= q32) l = 0.f; }
;                 zs[r] = z; l1[r] = l; }
;             float G0[4], G1[4];
; #pragma unroll
;             for (int j = 0; j < 4; ++j) { const float gs = (l1[4 * j] + l1[4 * j + 1]) + (l1[4 * j + 2] + l1[4 * j + 3]);
;                 auto rr = __builtin_amdgcn_permlane32_swap(__float_as_uint(gs), __float_as_uint(gs), false, false); G0[j] = __uint_as_float(rr[0]); G1[j] = __uint_as_float(rr[1]); }
.LBB0_304:
	v_add_u32_e32 v115, v49, v102
	ds_read_b128 v[0:3], v115
	ds_read_b128 v[16:19], v115 offset:32
	s_waitcnt lgkmcnt(1)
	v_mfma_f32_32x32x16_bf16 v[0:15], v[0:3], v[50:53], 0
	s_waitcnt lgkmcnt(0)
	v_mfma_f32_32x32x16_bf16 v[0:15], v[16:19], v[54:57], v[0:15]
	ds_read_b128 v[16:19], v115 offset:64
	s_waitcnt lgkmcnt(0)
	v_mfma_f32_32x32x16_bf16 v[0:15], v[16:19], v[58:61], v[0:15]
	ds_read_b128 v[16:19], v115 offset:96
	s_waitcnt lgkmcnt(0)
	v_mfma_f32_32x32x16_bf16 v[0:15], v[16:19], v[62:65], v[0:15]
	s_nop 11
	v_mul_f32_e32 v16, 0x3fb8aa3b, v2
	v_max_f32_e32 v17, 0, v16
	v_exp_f32_e64 v16, -|v16|
	v_mul_f32_e32 v11, 0x3fb8aa3b, v11
	v_exp_f32_e64 v21, -|v11|
	v_mul_f32_e32 v12, 0x3fb8aa3b, v12
	v_add_f32_e32 v16, 1.0, v16
	v_log_f32_e32 v16, v16
	v_add_f32_e32 v21, 1.0, v21
	v_log_f32_e32 v21, v21
	v_mul_f32_e32 v8, 0x3fb8aa3b, v8
	v_add_f32_e32 v17, v17, v16
	v_mul_f32_e32 v16, 0x3fb8aa3b, v3
	v_exp_f32_e64 v18, -|v16|
	v_max_f32_e32 v3, 0, v16
	v_mul_f32_e32 v4, 0x3fb8aa3b, v4
	v_mul_f32_e32 v0, 0x3fb8aa3b, v0
	v_add_f32_e32 v18, 1.0, v18
	v_log_f32_e32 v18, v18
	s_nop 0
	v_add_f32_e32 v3, v3, v18
	v_mul_f32_e32 v18, 0x3fb8aa3b, v6
	v_max_f32_e32 v19, 0, v18
	v_exp_f32_e64 v18, -|v18|
	s_nop 0
	v_add_f32_e32 v18, 1.0, v18
	v_log_f32_e32 v18, v18
	s_nop 0
	v_add_f32_e32 v18, v19, v18
	v_mul_f32_e32 v19, 0x3fb8aa3b, v10
	v_max_f32_e32 v20, 0, v19
	v_exp_f32_e64 v19, -|v19|
	s_nop 0
	v_add_f32_e32 v19, 1.0, v19
	v_log_f32_e32 v19, v19
	s_nop 0
	v_add_f32_e32 v19, v20, v19
	v_max_f32_e32 v20, 0, v11
	v_add_f32_e32 v24, v20, v21
	v_mul_f32_e32 v20, 0x3fb8aa3b, v14
	v_max_f32_e32 v21, 0, v20
	v_exp_f32_e64 v20, -|v20|
	s_nop 0
	v_add_f32_e32 v20, 1.0, v20
	v_log_f32_e32 v20, v20
	s_nop 0
	v_add_f32_e32 v21, v21, v20
	v_mul_f32_e32 v20, 0x3fb8aa3b, v15
	v_max_f32_e32 v22, 0, v20
	v_exp_f32_e64 v20, -|v20|
	s_nop 0
	v_add_f32_e32 v20, 1.0, v20
	v_log_f32_e32 v20, v20
	s_nop 0
	v_add_f32_e32 v20, v22, v20
	v_cndmask_b32_e64 v23, 0, -v20, s[36:37]
	v_exp_f32_e64 v20, -|v12|
	v_fmamk_f32 v25, v15, 0x3fb8aa3b, v23
	v_max_f32_e32 v15, 0, v12
	v_mul_f32_e32 v22, 0x3fb8aa3b, v13
	v_add_f32_e32 v20, 1.0, v20
	v_log_f32_e32 v20, v20
	v_max_f32_e32 v13, 0, v22
	v_add_f32_e32 v15, v15, v20
	v_cndmask_b32_e64 v20, 0, -v15, s[28:29]
	v_exp_f32_e64 v15, -|v22|
	s_nop 0
	v_add_f32_e32 v15, 1.0, v15
	v_log_f32_e32 v15, v15
	s_nop 0
	v_add_f32_e32 v13, v13, v15
	v_cndmask_b32_e64 v15, 0, -v21, s[34:35]
	v_fmamk_f32 v26, v14, 0x3fb8aa3b, v15
	v_cndmask_b32_e64 v14, 0, -v13, s[30:31]
	v_add_f32_e32 v21, v15, v23
	v_add_f32_e32 v13, v20, v14
	v_add_f32_e32 v27, v13, v21
	v_mov_b32_e32 v28, v27
	s_nop 1
	v_permlane32_swap_b32_e32 v27, v28
	v_add_f32_e32 v13, 0, v28
	v_cndmask_b32_e64 v13, 0, v13, s[38:39]
	v_add_f32_e32 v23, v13, v23
	v_add_f32_e32 v21, v13, v25
	v_add_f32_e32 v13, v23, v26
	v_exp_f32_e32 v13, v13
	v_pk_add_f32 v[22:23], v[22:23], v[14:15]
	v_exp_f32_e32 v21, v21
	v_cndmask_b32_e64 v15, 0, -v24, s[26:27]
	v_cndmask_b32_e64 v33, 0, v13, s[34:35]
	v_add_f32_e32 v13, v22, v23
	v_exp_f32_e32 v13, v13
	v_cndmask_b32_e64 v32, 0, v21, s[36:37]
	v_mov_b32_e32 v21, v14
	v_exp_f32_e64 v14, -|v8|
	v_cndmask_b32_e64 v34, 0, v13, s[30:31]
	v_mov_b32_e32 v13, v23
	v_pk_add_f32 v[12:13], v[12:13], v[20:21]
	v_add_f32_e32 v14, 1.0, v14
	v_add_f32_e32 v12, v12, v13
	v_exp_f32_e32 v12, v12
	v_log_f32_e32 v14, v14
	v_mul_f32_e32 v22, 0x3fb8aa3b, v9
	v_max_f32_e32 v9, 0, v22
	v_cndmask_b32_e64 v35, 0, v12, s[28:29]
	v_max_f32_e32 v12, 0, v8
	v_add_f32_e32 v12, v12, v14
	v_cndmask_b32_e64 v20, 0, -v12, s[20:21]
	v_exp_f32_e64 v12, -|v22|
	v_cndmask_b32_e64 v25, 0, -v19, s[24:25]
	v_fmamk_f32 v19, v10, 0x3fb8aa3b, v25
	v_add_f32_e32 v10, v25, v15
	v_add_f32_e32 v12, 1.0, v12
	v_log_f32_e32 v12, v12
	v_add_f32_e32 v13, v27, v28
	v_mov_b32_e32 v27, v48
	v_add_f32_e32 v9, v9, v12
	v_cndmask_b32_e64 v24, 0, -v9, s[22:23]
	v_add_f32_e32 v9, v20, v24
	v_add_f32_e32 v12, v9, v10
	v_mov_b32_e32 v26, v12
	s_nop 1
	v_permlane32_swap_b32_e32 v12, v26
	v_pk_add_f32 v[12:13], v[12:13], v[26:27]
	v_cndmask_b32_e64 v14, 0, v26, s[38:39]
	v_mov_b32_e32 v10, v13
	v_pk_add_f32 v[10:11], v[14:15], v[10:11]
	v_mov_b32_e32 v21, v24
	v_add_f32_e32 v9, v10, v11
	v_exp_f32_e32 v9, v9
	v_add_f32_e32 v23, v15, v10
	v_pk_add_f32 v[10:11], v[22:23], v[24:25]
	v_mov_b32_e32 v185, v13
	v_cndmask_b32_e64 v37, 0, v9, s[26:27]
	v_add_f32_e32 v9, v19, v23
	v_exp_f32_e32 v9, v9
	s_nop 0
; #define LAS __attribute__((address_space(3)))
; __device__ __forceinline__ unsigned pk2(float lo, float hi) { return pg8::cvt_pk_bf16(lo, hi); }
; __device__ __forceinline__ s16x4 vtr(LAS const unsigned char* p) { return __builtin_bit_cast(s16x4, __builtin_amdgcn_ds_read_tr16_b64_v4i16((LAS s16x4*)p)); }
; __device__ __forceinline__ void attn_phase(LAS unsigned char* lds, const bf16* Q, const bf16* K, const bf16* V, bf16* O, int cu, int G, int rev) {
;     ...
;             float p[16]; float run = R;
; #pragma unroll
;             for (int j = 3; j >= 0; --j) { float sfx = run + (hi == 0 ? G1[j] : 0.f);
; #pragma unroll
;                 for (int e = 3; e >= 0; --e) { const int r = 4 * j + e; float val = __builtin_amdgcn_exp2f(l1[r] + zs[r] + sfx);
;                     if (diag) { const int kl = 8 * j + 4 * hi + e; if (kl >= q32) val = 0.f; }
;                     p[r] = val; sfx += l1[r]; }
;                 run += G0[j] + G1[j]; }
;             R = run;
; #pragma unroll
;             for (int ks2 = 0; ks2 < 2; ++ks2) {
;                 u32x4 pw; pw.x = pk2(p[8 * ks2], p[8 * ks2 + 1]); pw.y = pk2(p[8 * ks2 + 2], p[8 * ks2 + 3]); pw.z = pk2(p[8 * ks2 + 4], p[8 * ks2 + 5]); pw.w = pk2(p[8 * ks2 + 6], p[8 * ks2 + 7]);
;                 const bf16x8 pb = __builtin_bit_cast(bf16x8, pw);
; #pragma unroll
;                 for (int dh = 0; dh < 2; ++dh) {
;                     LAS const unsigned char* va = Vs + (16 * ks2 + 4 * hi + (li >> 2)) * 192 + (32 * dh + 16 * ((lane >> 4) & 1) + 4 * (li & 3)) * 2;
;                     const s16x4 lo = vtr(va), hi4 = vtr(va + 8 * 192);
;                     const bf16x8 vf = (bf16x8){lo[0], lo[1], lo[2], lo[3], hi4[0], hi4[1], hi4[2], hi4[3]};
;                     if (dh == 0) o0 = __builtin_amdgcn_mfma_f32_32x32x16_bf16(vf, pb, o0, 0, 0, 0);
;                     else         o1 = __builtin_amdgcn_mfma_f32_32x32x16_bf16(vf, pb, o1, 0, 0, 0);
;                 }
;             }
;             asm volatile("s_waitcnt lgkmcnt(0)" ::: "memory");
;             if (__all(R < -150.0f)) break;
	v_cndmask_b32_e64 v38, 0, v9, s[24:25]
	v_add_f32_e32 v9, v10, v11
	v_exp_f32_e32 v9, v9
	s_nop 0
	v_cndmask_b32_e64 v36, 0, v9, s[22:23]
	v_mov_b32_e32 v9, v11
	v_pk_add_f32 v[8:9], v[8:9], v[20:21]
	v_mul_f32_e32 v20, 0x3fb8aa3b, v5
	v_add_f32_e32 v8, v8, v9
	v_exp_f32_e32 v8, v8
	v_max_f32_e32 v5, 0, v20
	v_cndmask_b32_e64 v39, 0, v8, s[20:21]
	v_pk_mov_b32 v[8:9], v[6:7], v[12:13] op_sel:[1,0]
	s_nop 0
	v_pk_mul_f32 v[10:11], v[8:9], v[184:185]
	v_pk_add_f32 v[8:9], v[8:9], v[184:185]
	v_max_f32_e32 v7, 0, v10
	v_exp_f32_e64 v8, -|v10|
	v_mov_b32_e32 v11, v9
	v_add_f32_e32 v8, 1.0, v8
	v_log_f32_e32 v8, v8
	s_nop 0
	v_add_f32_e32 v7, v7, v8
	v_exp_f32_e64 v8, -|v4|
	v_cndmask_b32_e64 v12, 0, -v7, s[18:19]
	v_max_f32_e32 v7, 0, v4
	v_add_f32_e32 v8, 1.0, v8
	v_log_f32_e32 v8, v8
	s_nop 0
	v_add_f32_e32 v7, v7, v8
	v_cndmask_b32_e64 v14, 0, -v7, s[12:13]
	v_exp_f32_e64 v7, -|v20|
	s_nop 0
	v_add_f32_e32 v7, 1.0, v7
	v_log_f32_e32 v7, v7
	s_nop 0
	v_add_f32_e32 v5, v5, v7
	v_cndmask_b32_e64 v7, 0, -v18, s[16:17]
	v_fmamk_f32 v15, v6, 0x3fb8aa3b, v7
	v_cndmask_b32_e64 v6, 0, -v5, s[14:15]
	v_add_f32_e32 v8, v7, v12
	v_add_f32_e32 v5, v14, v6
	v_add_f32_e32 v8, v5, v8
	v_mov_b32_e32 v18, v8
	s_nop 1
	v_permlane32_swap_b32_e32 v8, v18
	v_cndmask_b32_e64 v13, 0, v18, s[38:39]
	v_pk_add_f32 v[10:11], v[10:11], v[12:13]
	s_nop 0
	v_add_f32_e32 v5, v10, v11
	v_exp_f32_e32 v5, v5
	v_add_f32_e32 v21, v12, v11
	v_pk_add_f32 v[10:11], v[20:21], v[6:7]
	v_mul_f32_e32 v12, 0x3fb8aa3b, v1
	v_cndmask_b32_e64 v19, 0, v5, s[18:19]
	v_add_f32_e32 v5, v15, v21
	v_exp_f32_e32 v5, v5
	v_mov_b32_e32 v15, v6
	v_cndmask_b32_e64 v6, 0, -v3, s[10:11]
	v_max_f32_e32 v3, 0, v0
	v_cndmask_b32_e64 v22, 0, v5, s[16:17]
	v_add_f32_e32 v5, v10, v11
	v_exp_f32_e32 v5, v5
	v_max_f32_e32 v1, 0, v12
	v_cndmask_b32_e64 v20, 0, v5, s[14:15]
	v_mov_b32_e32 v5, v11
	v_pk_add_f32 v[4:5], v[4:5], v[14:15]
	s_nop 0
	v_add_f32_e32 v4, v4, v5
	v_exp_f32_e32 v4, v4
	v_add_f32_e32 v5, v8, v18
	v_cndmask_b32_e64 v14, 0, v4, s[12:13]
	v_exp_f32_e64 v4, -|v0|
	s_nop 0
	v_add_f32_e32 v4, 1.0, v4
	v_log_f32_e32 v4, v4
	s_nop 0
	v_add_f32_e32 v3, v3, v4
	v_cndmask_b32_e64 v10, 0, -v3, s[4:5]
	v_exp_f32_e64 v3, -|v12|
	s_nop 0
	v_add_f32_e32 v3, 1.0, v3
	v_log_f32_e32 v3, v3
	s_nop 0
	v_add_f32_e32 v1, v1, v3
	v_cndmask_b32_e64 v3, 0, -v17, s[8:9]
	v_fmamk_f32 v11, v2, 0x3fb8aa3b, v3
	v_cndmask_b32_e64 v2, 0, -v1, s[6:7]
	v_add_f32_e32 v4, v3, v6
	v_add_f32_e32 v1, v10, v2
	v_add_f32_e32 v4, v1, v4
	v_mov_b32_e32 v8, v4
	s_nop 1
	v_permlane32_swap_b32_e32 v4, v8
	v_pk_add_f32 v[40:41], v[4:5], v[8:9]
	v_cndmask_b32_e64 v7, 0, v8, s[38:39]
	v_mov_b32_e32 v17, v41
	v_pk_add_f32 v[4:5], v[16:17], v[6:7]
	v_add_f32_e32 v117, v40, v41
	v_add_f32_e32 v1, v4, v5
	v_exp_f32_e32 v1, v1
	v_add_f32_e32 v13, v6, v5
	v_pk_add_f32 v[4:5], v[12:13], v[2:3]
	v_cmp_gt_f32_e32 vcc, s48, v117
	v_cndmask_b32_e64 v7, 0, v1, s[10:11]
	v_add_f32_e32 v1, v11, v13
	v_exp_f32_e32 v1, v1
	v_mov_b32_e32 v11, v2
	s_cmp_eq_u64 vcc, exec
	s_cselect_b64 s[96:97], -1, 0
	v_cndmask_b32_e64 v6, 0, v1, s[8:9]
	v_add_f32_e32 v1, v4, v5
	v_exp_f32_e32 v1, v1
	s_xor_b64 s[64:65], s[64:65], -1
	s_or_b64 s[64:65], s[64:65], s[96:97]
	s_and_b64 vcc, exec, s[64:65]
	v_cndmask_b32_e64 v3, 0, v1, s[6:7]
	v_mov_b32_e32 v1, v5
	v_pk_add_f32 v[0:1], v[0:1], v[10:11]
	s_nop 0
	v_add_f32_e32 v0, v0, v1
	v_exp_f32_e32 v0, v0
	s_nop 0
	v_cndmask_b32_e64 v0, 0, v0, s[4:5]
	v_cvt_pk_bf16_f32 v16, v0, v3
	v_cvt_pk_bf16_f32 v17, v6, v7
	v_cvt_pk_bf16_f32 v18, v14, v20
	v_cvt_pk_bf16_f32 v19, v22, v19
	ds_read_b64_tr_b16 v[0:1], v113 offset:4608
	ds_read_b64_tr_b16 v[2:3], v113 offset:6144
	s_waitcnt lgkmcnt(0)
	v_mfma_f32_32x32x16_bf16 v[0:15], v[0:3], v[16:19], 0
	ds_read_b64_tr_b16 v[20:21], v113 offset:4672
	ds_read_b64_tr_b16 v[22:23], v113 offset:6208
	v_cvt_pk_bf16_f32 v36, v39, v36
	v_cvt_pk_bf16_f32 v37, v38, v37
	v_cvt_pk_bf16_f32 v38, v35, v34
	v_cvt_pk_bf16_f32 v39, v33, v32
	ds_read_b64_tr_b16 v[32:33], v113 offset:7680
	ds_read_b64_tr_b16 v[34:35], v113 offset:9216
	s_waitcnt lgkmcnt(2)
	v_mfma_f32_32x32x16_bf16 v[16:31], v[20:23], v[16:19], 0
	s_waitcnt lgkmcnt(0)
	v_mfma_f32_32x32x16_bf16 v[0:15], v[32:35], v[36:39], v[0:15]
	ds_read_b64_tr_b16 v[32:33], v113 offset:7744
	ds_read_b64_tr_b16 v[34:35], v113 offset:9280
	s_waitcnt lgkmcnt(0)
	s_waitcnt lgkmcnt(0)
	v_mfma_f32_32x32x16_bf16 v[16:31], v[32:35], v[36:39], v[16:31]
	s_cbranch_vccz .LBB0_307

; #define LAS __attribute__((address_space(3)))
; __device__ __forceinline__ void attn_phase(LAS unsigned char* lds, const bf16* Q, const bf16* K, const bf16* V, bf16* O, int cu, int G, int rev) {
;     ...
;         for (int key0 = q0w; key0 >= 0; key0 -= 32) {
; #pragma unroll
;             for (int jj = 0; jj < 4; ++jj) { *(LAS u32x4*)(Ks + (lkey + 8 * jj) * 144 + lch * 16) = kr[jj]; *(LAS u32x4*)(Vs + (lkey + 8 * jj) * 192 + lch * 16) = vr[jj]; }
;             asm volatile("s_waitcnt lgkmcnt(0)" ::: "memory");
;             if (key0 >= 32) {
; #pragma unroll
;                 for (int jj = 0; jj < 4; ++jj) { kr[jj] = *(const u32x4*)(kp + (size_t)(key0 - 32 + 8 * jj) * DM); vr[jj] = *(const u32x4*)(vp + (size_t)(key0 - 32 + 8 * jj) * DM); } }
.LBB0_307:
	s_cmp_lt_i32 s62, 64
	s_cbranch_scc1 .Lmy_at_b_short
	s_waitcnt vmcnt(15)
	ds_write_b128 v101, v[208:211]
	s_waitcnt vmcnt(14)
	ds_write_b128 v103, v[212:215] offset:4608
	s_waitcnt vmcnt(13)
	ds_write_b128 v101, v[216:219] offset:1152
	s_waitcnt vmcnt(12)
	ds_write_b128 v103, v[220:223] offset:6144
	s_waitcnt vmcnt(11)
	ds_write_b128 v101, v[224:227] offset:2304
	s_waitcnt vmcnt(10)
	ds_write_b128 v103, v[228:231] offset:7680
	s_waitcnt vmcnt(9)
	ds_write_b128 v101, v[232:235] offset:3456
	s_waitcnt vmcnt(8)
	ds_write_b128 v103, v[236:239] offset:9216
	s_branch .Lmy_at_b_wr
.Lmy_at_b_short:
	s_waitcnt vmcnt(7)
	ds_write_b128 v101, v[208:211]
	s_waitcnt vmcnt(6)
	ds_write_b128 v103, v[212:215] offset:4608
	s_waitcnt vmcnt(5)
	ds_write_b128 v101, v[216:219] offset:1152
	s_waitcnt vmcnt(4)
	ds_write_b128 v103, v[220:223] offset:6144
	s_waitcnt vmcnt(3)
	ds_write_b128 v101, v[224:227] offset:2304
	s_waitcnt vmcnt(2)
	ds_write_b128 v103, v[228:231] offset:7680
	s_waitcnt vmcnt(1)
	ds_write_b128 v101, v[232:235] offset:3456
	s_waitcnt vmcnt(0)
	ds_write_b128 v103, v[236:239] offset:9216
.Lmy_at_b_wr:
	s_waitcnt lgkmcnt(0)
	s_cmp_gt_i32 s62, 63
	s_cselect_b64 s[64:65], -1, 0
	s_cmp_lt_i32 s62, 96
	s_cbranch_scc1 .Lmy_at_body1
	s_sub_i32 s44, s62, 96
	s_lshl_b64 s[96:97], s[44:45], 11
	v_lshl_add_u64 v[32:33], v[118:119], 0, s[96:97]
	v_lshl_add_u64 v[34:35], v[120:121], 0, s[96:97]
	global_load_dwordx4 v[208:211], v[32:33], off
	global_load_dwordx4 v[212:215], v[34:35], off
	s_sub_i32 s44, s62, 88
	s_lshl_b64 s[96:97], s[44:45], 11
	v_lshl_add_u64 v[32:33], v[118:119], 0, s[96:97]
	v_lshl_add_u64 v[34:35], v[120:121], 0, s[96:97]
	global_load_dwordx4 v[216:219], v[32:33], off
	global_load_dwordx4 v[220:223], v[34:35], off
	s_sub_i32 s44, s62, 80
	s_lshl_b64 s[96:97], s[44:45], 11
	v_lshl_add_u64 v[32:33], v[118:119], 0, s[96:97]
	v_lshl_add_u64 v[34:35], v[120:121], 0, s[96:97]
	global_load_dwordx4 v[224:227], v[32:33], off
	global_load_dwordx4 v[228:231], v[34:35], off
	s_sub_i32 s44, s62, 72
	s_lshl_b64 s[96:97], s[44:45], 11
	v_lshl_add_u64 v[32:33], v[118:119], 0, s[96:97]
	v_lshl_add_u64 v[34:35], v[120:121], 0, s[96:97]
	global_load_dwordx4 v[232:235], v[32:33], off
	global_load_dwordx4 v[236:239], v[34:35], off

; #define LAS __attribute__((address_space(3)))
; __device__ __forceinline__ void attn_phase(LAS unsigned char* lds, const bf16* Q, const bf16* K, const bf16* V, bf16* O, int cu, int G, int rev) {
;     ...
;             for (int jj = 0; jj < 4; ++jj) { *(LAS u32x4*)(Ks + (lkey + 8 * jj) * 144 + lch * 16) = kr[jj]; *(LAS u32x4*)(Vs + (lkey + 8 * jj) * 192 + lch * 16) = vr[jj]; }
;             asm volatile("s_waitcnt lgkmcnt(0)" ::: "memory");
.Lmy_at_topA:
	s_cmp_lt_i32 s62, 64
	s_cbranch_scc1 .Lmy_at_a_short
	s_waitcnt vmcnt(15)
	ds_write_b128 v101, v[66:69]
	s_waitcnt vmcnt(14)
	ds_write_b128 v103, v[70:73] offset:4608
	s_waitcnt vmcnt(13)
	ds_write_b128 v101, v[74:77] offset:1152
	s_waitcnt vmcnt(12)
	ds_write_b128 v103, v[78:81] offset:6144
	s_waitcnt vmcnt(11)
	ds_write_b128 v101, v[82:85] offset:2304
	s_waitcnt vmcnt(10)
	ds_write_b128 v103, v[86:89] offset:7680
	s_waitcnt vmcnt(9)
	ds_write_b128 v101, v[90:93] offset:3456
	s_waitcnt vmcnt(8)
	ds_write_b128 v103, v[94:97] offset:9216
	s_branch .Lmy_at_a_wr

; #define LAS __attribute__((address_space(3)))
; __device__ __forceinline__ void attn_phase(LAS unsigned char* lds, const bf16* Q, const bf16* K, const bf16* V, bf16* O, int cu, int G, int rev) {
;     ...
;             if (key0 >= 32) {
; #pragma unroll
;                 for (int jj = 0; jj < 4; ++jj) { kr[jj] = *(const u32x4*)(kp + (size_t)(key0 - 32 + 8 * jj) * DM); vr[jj] = *(const u32x4*)(vp + (size_t)(key0 - 32 + 8 * jj) * DM); } }
;             const bool diag = (key0 == q0w);
;             f32x16 s;
; #pragma unroll
;             for (int r = 0; r < 16; ++r) s[r] = 0.f;
; #pragma unroll
;             for (int ks = 0; ks < 4; ++ks) { const bf16x8 kf = *(LAS const bf16x8*)(Ks + q32 * 144 + (16 * ks + 8 * hi) * 2);
;                 s = __builtin_amdgcn_mfma_f32_32x32x16_bf16(kf, qf[ks], s, 0, 0, 0); }
;             float zs[16], l1[16];
; #pragma unroll
;             for (int r = 0; r < 16; ++r) { const float z = s[r] * LOG2E; const float e = __builtin_amdgcn_exp2f(-__builtin_fabsf(z)); const float t = __builtin_amdgcn_logf(1.0f + e);
;                 float l = -(__builtin_fmaxf(z, 0.f) + t);
;                 if (diag) { const int kl = 8 * (r >> 2) + 4 * hi + (r & 3); if (kl >= q32) l = 0.f; }
;                 zs[r] = z; l1[r] = l; }
;             float G0[4], G1[4];
; #pragma unroll
;             for (int j = 0; j < 4; ++j) { const float gs = (l1[4 * j] + l1[4 * j + 1]) + (l1[4 * j + 2] + l1[4 * j + 3]);
;                 auto rr = __builtin_amdgcn_permlane32_swap(__float_as_uint(gs), __float_as_uint(gs), false, false); G0[j] = __uint_as_float(rr[0]); G1[j] = __uint_as_float(rr[1]); }
.Lmy_at_a_wr:
	s_waitcnt lgkmcnt(0)
	s_cmp_gt_i32 s62, 63
	s_cselect_b64 s[64:65], -1, 0
	s_cmp_lt_i32 s62, 96
	s_cbranch_scc1 .Lmy_at_body2
	s_sub_i32 s44, s62, 96
	s_lshl_b64 s[96:97], s[44:45], 11
	v_lshl_add_u64 v[32:33], v[118:119], 0, s[96:97]
	v_lshl_add_u64 v[34:35], v[120:121], 0, s[96:97]
	global_load_dwordx4 v[66:69], v[32:33], off
	global_load_dwordx4 v[70:73], v[34:35], off
	s_sub_i32 s44, s62, 88
	s_lshl_b64 s[96:97], s[44:45], 11
	v_lshl_add_u64 v[32:33], v[118:119], 0, s[96:97]
	v_lshl_add_u64 v[34:35], v[120:121], 0, s[96:97]
	global_load_dwordx4 v[74:77], v[32:33], off
	global_load_dwordx4 v[78:81], v[34:35], off
	s_sub_i32 s44, s62, 80
	s_lshl_b64 s[96:97], s[44:45], 11
	v_lshl_add_u64 v[32:33], v[118:119], 0, s[96:97]
	v_lshl_add_u64 v[34:35], v[120:121], 0, s[96:97]
	global_load_dwordx4 v[82:85], v[32:33], off
	global_load_dwordx4 v[86:89], v[34:35], off
	s_sub_i32 s44, s62, 72
	s_lshl_b64 s[96:97], s[44:45], 11
	v_lshl_add_u64 v[32:33], v[118:119], 0, s[96:97]
	v_lshl_add_u64 v[34:35], v[120:121], 0, s[96:97]
	global_load_dwordx4 v[90:93], v[32:33], off
	global_load_dwordx4 v[94:97], v[34:35], off
.Lmy_at_body2:
	ds_read_b128 v[32:35], v115
	ds_read_b128 v[122:125], v115 offset:32
	s_waitcnt lgkmcnt(1)
	v_mfma_f32_32x32x16_bf16 v[32:47], v[32:35], v[50:53], 0
	s_waitcnt lgkmcnt(0)
	v_mfma_f32_32x32x16_bf16 v[32:47], v[122:125], v[54:57], v[32:47]
	ds_read_b128 v[122:125], v115 offset:64
	ds_read_b128 v[126:129], v115 offset:96
	s_waitcnt lgkmcnt(1)
	v_mfma_f32_32x32x16_bf16 v[32:47], v[122:125], v[58:61], v[32:47]
	s_waitcnt lgkmcnt(0)
	v_mfma_f32_32x32x16_bf16 v[32:47], v[126:129], v[62:65], v[32:47]
	s_nop 11
	v_mul_f32_e32 v123, 0x3fb8aa3b, v35
	v_mul_f32_e32 v126, 0x3fb8aa3b, v37
	v_mul_f32_e32 v42, 0x3fb8aa3b, v42
	v_mul_f32_e32 v127, 0x3fb8aa3b, v43
	v_exp_f32_e64 v134, -|v123|
	v_max_f32_e32 v129, 0, v123
	v_exp_f32_e64 v123, -|v126|
	v_exp_f32_e64 v137, -|v42|
	v_exp_f32_e64 v140, -|v127|
	v_mul_f32_e32 v46, 0x3fb8aa3b, v46
	v_add_f32_e32 v123, 1.0, v123
	v_add_f32_e32 v142, 1.0, v137
	v_log_f32_e32 v137, v123
	v_add_f32_e32 v123, 1.0, v140
	v_mul_f32_e32 v124, 0x3fb8aa3b, v34
	v_mul_f32_e32 v38, 0x3fb8aa3b, v38
	v_mul_f32_e32 v125, 0x3fb8aa3b, v39
	v_mul_f32_e32 v34, 0x3fb8aa3b, v41
	v_log_f32_e32 v143, v123
	v_exp_f32_e64 v123, -|v46|
	v_exp_f32_e64 v133, -|v124|
	v_exp_f32_e64 v135, -|v38|
	v_exp_f32_e64 v136, -|v125|
	v_max_f32_e32 v131, 0, v125
	v_exp_f32_e64 v125, -|v34|
	v_add_f32_e32 v123, 1.0, v123
	v_add_f32_e32 v138, 1.0, v133
	v_add_f32_e32 v141, 1.0, v135
	v_add_f32_e32 v125, 1.0, v125
	v_mul_f32_e32 v146, 0x3fb8aa3b, v45
	v_log_f32_e32 v150, v123
	v_mul_f32_e32 v123, 0x3fb8aa3b, v47
	v_mul_f32_e32 v154, 0x3fb8aa3b, v44
	v_add_f32_e32 v139, 1.0, v134
	v_log_f32_e32 v134, v138
	v_log_f32_e32 v138, v141
	v_log_f32_e32 v141, v125
	v_exp_f32_e64 v45, -|v146|
	v_exp_f32_e64 v125, -|v123|
	v_exp_f32_e64 v44, -|v154|
	v_max_f32_e32 v149, 0, v146
	v_add_f32_e32 v45, 1.0, v45
	v_add_f32_e32 v125, 1.0, v125
	v_add_f32_e32 v44, 1.0, v44
	v_log_f32_e32 v45, v45
	v_log_f32_e32 v151, v125
	v_log_f32_e32 v44, v44
	v_max_f32_e32 v152, 0, v46
	v_max_f32_e32 v153, 0, v123
	v_max_f32_e32 v148, 0, v154
	v_pk_add_f32 v[150:151], v[152:153], v[150:151]
	v_pk_add_f32 v[44:45], v[148:149], v[44:45]
	v_mov_b32_e32 v149, v151
	v_mov_b32_e32 v148, v45
	v_mov_b32_e32 v152, v44
	v_mov_b32_e32 v153, v150
	v_pk_add_f32 v[148:149], v[148:149], v[152:153] neg_lo:[1,1] neg_hi:[1,1]
	v_fma_f32 v123, v47, s81, -v151
	v_pk_add_f32 v[148:149], v[148:149], v[148:149] op_sel:[0,1] op_sel_hi:[1,0]
	v_log_f32_e32 v142, v142
	v_mov_b32_e32 v125, v148
	s_nop 1
	v_permlane32_swap_b32_e32 v148, v125
	v_cndmask_b32_e64 v47, 0, v125, s[38:39]
	v_add_f32_e32 v47, v117, v47
	v_add_f32_e32 v123, v47, v123
	v_pk_add_f32 v[46:47], v[46:47], v[150:151] neg_lo:[0,1] neg_hi:[0,1]
	v_max_f32_e32 v144, 0, v42
	v_add_f32_e32 v46, v46, v47
	v_exp_f32_e32 v152, v46
	v_mov_b32_e32 v147, v47
	v_pk_mov_b32 v[46:47], v[44:45], v[150:151] op_sel:[1,0]
	v_max_f32_e32 v145, 0, v127
	v_pk_add_f32 v[46:47], v[146:147], v[46:47] neg_lo:[0,1] neg_hi:[0,1]
	v_mul_f32_e32 v146, 0x3fb8aa3b, v40
	v_exp_f32_e64 v40, -|v146|
	v_pk_add_f32 v[142:143], v[144:145], v[142:143]
	v_mul_f32_e32 v144, 0x3fb8aa3b, v36
	v_exp_f32_e64 v36, -|v144|
	v_add_f32_e32 v40, 1.0, v40
	v_log_f32_e32 v140, v40
	v_max_f32_e32 v41, 0, v34
	v_max_f32_e32 v40, 0, v146
	v_add_f32_e32 v46, v46, v47
	v_pk_add_f32 v[40:41], v[40:41], v[140:141]
	v_add_f32_e32 v136, 1.0, v136
	v_exp_f32_e32 v150, v46
	v_mov_b32_e32 v155, v47
	v_mov_b32_e32 v46, v41
	v_mov_b32_e32 v47, v143
	v_mov_b32_e32 v140, v40
	v_mov_b32_e32 v141, v142
	v_add_f32_e32 v36, 1.0, v36
	v_log_f32_e32 v135, v139
	v_log_f32_e32 v139, v136
	v_pk_add_f32 v[46:47], v[46:47], v[140:141] neg_lo:[1,1] neg_hi:[1,1]
	v_log_f32_e32 v136, v36
	v_pk_add_f32 v[44:45], v[154:155], v[44:45] neg_lo:[0,1] neg_hi:[0,1]
; #define LAS __attribute__((address_space(3)))
; __device__ __forceinline__ unsigned pk2(float lo, float hi) { return pg8::cvt_pk_bf16(lo, hi); }
; __device__ __forceinline__ s16x4 vtr(LAS const unsigned char* p) { return __builtin_bit_cast(s16x4, __builtin_amdgcn_ds_read_tr16_b64_v4i16((LAS s16x4*)p)); }
; __device__ __forceinline__ void attn_phase(LAS unsigned char* lds, const bf16* Q, const bf16* K, const bf16* V, bf16* O, int cu, int G, int rev) {
;     ...
;             float p[16]; float run = R;
; #pragma unroll
;             for (int j = 3; j >= 0; --j) { float sfx = run + (hi == 0 ? G1[j] : 0.f);
; #pragma unroll
;                 for (int e = 3; e >= 0; --e) { const int r = 4 * j + e; float val = __builtin_amdgcn_exp2f(l1[r] + zs[r] + sfx);
;                     if (diag) { const int kl = 8 * j + 4 * hi + e; if (kl >= q32) val = 0.f; }
;                     p[r] = val; sfx += l1[r]; }
;                 run += G0[j] + G1[j]; }
;             R = run;
; #pragma unroll
;             for (int ks2 = 0; ks2 < 2; ++ks2) {
;                 u32x4 pw; pw.x = pk2(p[8 * ks2], p[8 * ks2 + 1]); pw.y = pk2(p[8 * ks2 + 2], p[8 * ks2 + 3]); pw.z = pk2(p[8 * ks2 + 4], p[8 * ks2 + 5]); pw.w = pk2(p[8 * ks2 + 6], p[8 * ks2 + 7]);
;                 const bf16x8 pb = __builtin_bit_cast(bf16x8, pw);
; #pragma unroll
;                 for (int dh = 0; dh < 2; ++dh) {
;                     LAS const unsigned char* va = Vs + (16 * ks2 + 4 * hi + (li >> 2)) * 192 + (32 * dh + 16 * ((lane >> 4) & 1) + 4 * (li & 3)) * 2;
;                     const s16x4 lo = vtr(va), hi4 = vtr(va + 8 * 192);
;                     const bf16x8 vf = (bf16x8){lo[0], lo[1], lo[2], lo[3], hi4[0], hi4[1], hi4[2], hi4[3]};
;                     if (dh == 0) o0 = __builtin_amdgcn_mfma_f32_32x32x16_bf16(vf, pb, o0, 0, 0, 0);
;                     else         o1 = __builtin_amdgcn_mfma_f32_32x32x16_bf16(vf, pb, o1, 0, 0, 0);
;                 }
;             }
;             asm volatile("s_waitcnt lgkmcnt(0)" ::: "memory");
;             if (__all(R < -150.0f)) break;
	v_pk_add_f32 v[46:47], v[46:47], v[46:47] op_sel:[0,1] op_sel_hi:[1,0]
	v_add_f32_e32 v151, v44, v45
	v_mov_b32_e32 v44, v46
	v_max_f32_e32 v37, 0, v126
	v_max_f32_e32 v130, 0, v38
	v_add_f32_e32 v45, v148, v125
	v_permlane32_swap_b32_e32 v46, v44
	v_mov_b32_e32 v47, v117
	v_max_f32_e32 v36, 0, v144
	v_exp_f32_e32 v149, v123
	v_fma_f32 v123, v43, s81, -v143
	v_cndmask_b32_e64 v43, 0, v44, s[38:39]
	v_pk_add_f32 v[44:45], v[46:47], v[44:45]
	v_pk_add_f32 v[46:47], v[130:131], v[138:139]
	v_pk_add_f32 v[36:37], v[36:37], v[136:137]
	v_mov_b32_e32 v131, v47
	v_mov_b32_e32 v130, v37
	v_mov_b32_e32 v136, v36
	v_mov_b32_e32 v137, v46
	v_pk_add_f32 v[130:131], v[130:131], v[136:137] neg_lo:[1,1] neg_hi:[1,1]
	v_add_f32_e32 v43, v43, v45
	v_pk_add_f32 v[130:131], v[130:131], v[130:131] op_sel:[0,1] op_sel_hi:[1,0]
	v_mov_b32_e32 v137, v45
	v_mov_b32_e32 v136, v130
	s_nop 1
	v_permlane32_swap_b32_e32 v130, v136
	v_mov_b32_e32 v131, v44
	v_add_f32_e32 v117, v123, v43
	v_fma_f32 v123, v39, s81, -v47
	v_cndmask_b32_e64 v39, 0, v136, s[38:39]
	v_pk_add_f32 v[44:45], v[130:131], v[136:137]
	v_pk_mov_b32 v[138:139], v[36:37], v[46:47] op_sel:[1,0]
	v_add_f32_e32 v39, v39, v45
	v_add_f32_e32 v123, v123, v39
	v_pk_add_f32 v[38:39], v[38:39], v[46:47] neg_lo:[0,1] neg_hi:[0,1]
	v_mul_f32_e32 v122, 0x3fb8aa3b, v33
	v_mov_b32_e32 v127, v39
	v_add_f32_e32 v131, v38, v39
	v_pk_add_f32 v[38:39], v[126:127], v[138:139] neg_lo:[0,1] neg_hi:[0,1]
	v_exp_f32_e64 v132, -|v122|
	v_add_f32_e32 v38, v38, v39
	v_exp_f32_e32 v136, v38
	v_mul_f32_e32 v38, 0x3fb8aa3b, v32
	v_exp_f32_e64 v32, -|v38|
	v_add_f32_e32 v132, 1.0, v132
	v_log_f32_e32 v133, v132
	v_mov_b32_e32 v145, v39
	v_add_f32_e32 v32, 1.0, v32
	v_log_f32_e32 v132, v32
	v_max_f32_e32 v33, 0, v122
	v_max_f32_e32 v128, 0, v124
	v_pk_add_f32 v[36:37], v[144:145], v[36:37] neg_lo:[0,1] neg_hi:[0,1]
	v_max_f32_e32 v32, 0, v38
	v_add_f32_e32 v137, v36, v37
	v_pk_add_f32 v[36:37], v[128:129], v[134:135]
	v_pk_add_f32 v[32:33], v[32:33], v[132:133]
	v_mov_b32_e32 v47, v37
	v_mov_b32_e32 v46, v33
	v_mov_b32_e32 v126, v32
	v_mov_b32_e32 v127, v36
	v_pk_add_f32 v[46:47], v[46:47], v[126:127] neg_lo:[1,1] neg_hi:[1,1]
	v_mov_b32_e32 v127, v45
	v_pk_add_f32 v[46:47], v[46:47], v[46:47] op_sel:[0,1] op_sel_hi:[1,0]
	v_fma_f32 v35, v35, s81, -v37
	v_mov_b32_e32 v126, v46
	s_nop 1
	v_permlane32_swap_b32_e32 v46, v126
	v_mov_b32_e32 v47, v44
	v_cndmask_b32_e64 v39, 0, v126, s[38:39]
	v_pk_add_f32 v[126:127], v[46:47], v[126:127]
	v_pk_mov_b32 v[128:129], v[32:33], v[36:37] op_sel:[1,0]
	v_add_f32_e32 v125, v39, v127
	v_pk_add_f32 v[36:37], v[124:125], v[36:37] neg_lo:[0,1] neg_hi:[0,1]
	v_exp_f32_e32 v130, v123
	v_mov_b32_e32 v123, v37
	v_add_f32_e32 v44, v36, v37
	v_pk_add_f32 v[36:37], v[122:123], v[128:129] neg_lo:[0,1] neg_hi:[0,1]
	v_add_f32_e32 v35, v35, v125
	v_mov_b32_e32 v39, v37
	v_pk_add_f32 v[32:33], v[38:39], v[32:33] neg_lo:[0,1] neg_hi:[0,1]
	v_add_f32_e32 v36, v36, v37
	v_add_f32_e32 v32, v32, v33
	v_exp_f32_e32 v36, v36
	v_exp_f32_e32 v32, v32
	v_exp_f32_e32 v33, v44
	v_exp_f32_e32 v35, v35
	v_cvt_pk_bf16_f32 v36, v32, v36
	v_cvt_pk_bf16_f32 v37, v33, v35
	v_pk_add_f32 v[32:33], v[42:43], v[142:143] neg_lo:[0,1] neg_hi:[0,1]
	v_pk_mov_b32 v[140:141], v[40:41], v[142:143] op_sel:[1,0]
	v_exp_f32_e32 v38, v137
	v_exp_f32_e32 v39, v131
	v_mov_b32_e32 v35, v33
	v_cvt_pk_bf16_f32 v38, v38, v136
	v_cvt_pk_bf16_f32 v39, v39, v130
	ds_read_b64_tr_b16 v[44:45], v113 offset:4608
	ds_read_b64_tr_b16 v[46:47], v113 offset:6144
	v_add_f32_e32 v122, v32, v33
	v_pk_add_f32 v[42:43], v[34:35], v[140:141] neg_lo:[0,1] neg_hi:[0,1]
	ds_read_b64_tr_b16 v[34:35], v113 offset:6208
	ds_read_b64_tr_b16 v[32:33], v113 offset:4672
	v_mov_b32_e32 v147, v43
	s_waitcnt lgkmcnt(2)
	v_mfma_f32_32x32x16_bf16 v[0:15], v[44:47], v[36:39], v[0:15]
	v_add_f32_e64 v40, v146, -v40
	v_add_f32_e64 v41, v147, -v41
	v_add_f32_e32 v42, v42, v43
	v_add_f32_e32 v40, v40, v41
	v_exp_f32_e32 v42, v42
	v_exp_f32_e32 v40, v40
	v_exp_f32_e32 v41, v122
	v_exp_f32_e32 v43, v151
	s_waitcnt lgkmcnt(0)
	v_mfma_f32_32x32x16_bf16 v[16:31], v[32:35], v[36:39], v[16:31]
	v_exp_f32_e32 v117, v117
	v_cvt_pk_bf16_f32 v32, v40, v42
	v_cvt_pk_bf16_f32 v33, v41, v117
	v_cvt_pk_bf16_f32 v34, v43, v150
	v_cvt_pk_bf16_f32 v35, v152, v149
	ds_read_b64_tr_b16 v[36:37], v113 offset:7680
	ds_read_b64_tr_b16 v[38:39], v113 offset:9216
	ds_read_b64_tr_b16 v[42:43], v113 offset:9280
	ds_read_b64_tr_b16 v[40:41], v113 offset:7744
	v_add_f32_e32 v117, v126, v127
	s_waitcnt lgkmcnt(2)
	v_mfma_f32_32x32x16_bf16 v[0:15], v[36:39], v[32:35], v[0:15]
	v_cmp_gt_f32_e32 vcc, s48, v117
	s_cmp_lg_u64 vcc, exec
	s_waitcnt lgkmcnt(0)
	s_cselect_b64 s[96:97], -1, 0
	s_and_b64 s[64:65], s[64:65], s[96:97]
	s_sub_i32 s62, s62, 32
	s_and_b64 vcc, exec, s[64:65]
	s_waitcnt lgkmcnt(0)
	v_mfma_f32_32x32x16_bf16 v[16:31], v[40:43], v[32:35], v[16:31]
	s_cbranch_vccz .LBB0_305
	s_branch .LBB0_307
